# grid barrier spin-wait tightening: s_sleep removed from the two TOPGEN poll loops
# speedup vs baseline: 1.0037x; 1.0002x over previous
.LBB0_650:
	s_and_b32 s3, s2, 0xff
	s_mov_b64 s[12:13], -1
	s_cmp_lg_u32 s3, 0
	s_mov_b64 s[16:17], -1
	s_nop 0
	s_cbranch_scc0 .LBB0_653
	s_and_b64 vcc, exec, s[16:17]
	s_cbranch_vccz .LBB0_649
